# P0c modulation loop: all sc/sh vector loads in flight (de-serialized), on top of previous
# baseline (speedup 1.0000x reference)
; #define GAS __attribute__((address_space(1)))
; __device__ __forceinline__ unsigned pk2(float lo, float hi) { const f32x2_t v = {lo, hi}; const bf16x2_t b = __builtin_convertvector(v, bf16x2_t); return __builtin_bit_cast(unsigned, b); }
; __device__ __forceinline__ int xb_lane() { int z = 0; asm volatile("" : "+v"(z)); return (int)__builtin_amdgcn_mbcnt_hi(~0u, __builtin_amdgcn_mbcnt_lo(~0u, (unsigned)z)); }
; __device__ __forceinline__ const float* row_input(const Frame& F, int row) { return row < ML ? FIN(0) + (size_t)row * DM : FIN(2) + (size_t)(row - ML) * DM; }
; __device__ __forceinline__ void store_modulated(const f32x4 (&v)[8], const float* sc, const float* sh, bf16* hrow, int lane) {
; #pragma unroll
;     for (int j = 0; j < 8; ++j) { const int c = 4 * lane + 256 * j; const f32x4 s = *(const GAS f32x4*)(sc + c), t = *(const GAS f32x4*)(sh + c);
;         const f32x4 o = v[j] * (s + 1.0f) + t; v2u w; w.x = pk2(o[0], o[1]); w.y = pk2(o[2], o[3]); *(GAS v2u*)(hrow + c) = w; }
; }
; __device__ __forceinline__ void p0c_modulate(Frame& FF) {
;     Frame F = FF; F.lane = xb_lane(); F.tid = F.wave * 64 + F.lane;
;     const float* mo = (const float*)(F.ws + WS_MOD); bf16* H = (bf16*)(F.ws + WS_H);
;     for (int row = F.vcu * NWAVES + F.wave; row < MT; row += F.G * NWAVES) { const float* xr = row_input(F, row); const float* mb = mo + (size_t)row_modb(row) * 12288;
;         f32x4 v[8];
; #pragma unroll
;         for (int j = 0; j < 8; ++j) v[j] = *(const GAS f32x4*)(xr + 4 * F.lane + 256 * j);
;         store_modulated(v, mb + 1 * 2048, mb + 0 * 2048, H + (size_t)row * DM, F.lane); }
.LBB0_231:
	s_load_dwordx2 s[10:11], s[10:11], 0x0
	s_lshl_b64 s[12:13], s[12:13], 13
	s_waitcnt lgkmcnt(0)
	s_add_u32 s10, s10, s12
	s_addc_u32 s11, s11, s13
	s_min_i32 s2, s6, 0x2000
	s_ashr_i32 s2, s2, 11
	v_lshl_add_u64 v[28:29], s[10:11], 0, v[2:3]
	s_mul_hi_i32 s11, s2, 0xc000
	s_mul_i32 s2, s2, 0xc000
	s_add_u32 s10, s16, s2
	s_addc_u32 s11, s17, s11
	v_lshl_add_u64 v[46:47], s[10:11], 0, v[2:3]
	v_add_co_u32_e32 v48, vcc, s21, v46
	s_lshl_b64 s[8:9], s[8:9], 12
	s_nop 0
	v_addc_co_u32_e32 v49, vcc, 0, v47, vcc
	global_load_dwordx4 v[4:7], v[48:49], off offset:-4096
	global_load_dwordx4 v[8:11], v[46:47], off
	global_load_dwordx4 v[12:15], v[28:29], off
	global_load_dwordx4 v[16:19], v[28:29], off offset:1024
	global_load_dwordx4 v[20:23], v[28:29], off offset:2048
	global_load_dwordx4 v[24:27], v[28:29], off offset:3072
	v_add_co_u32_e32 v50, vcc, s20, v28
	v_lshl_add_u64 v[52:53], v[46:47], 0, s[4:5]
	s_nop 0
	v_addc_co_u32_e32 v51, vcc, 0, v29, vcc
	global_load_dwordx4 v[28:31], v[50:51], off
	global_load_dwordx4 v[32:35], v[50:51], off offset:1024
	global_load_dwordx4 v[36:39], v[50:51], off offset:2048
	global_load_dwordx4 v[40:43], v[50:51], off offset:3072
	v_add_co_u32_e32 v54, vcc, s20, v46
	s_nop 1
	v_addc_co_u32_e32 v55, vcc, 0, v47, vcc
	global_load_dwordx4 v[64:67], v[52:53], off offset:1024
	global_load_dwordx4 v[92:95], v[46:47], off offset:1024
	global_load_dwordx4 v[68:71], v[52:53], off offset:2048
	global_load_dwordx4 v[96:99], v[46:47], off offset:2048
	global_load_dwordx4 v[72:75], v[52:53], off offset:3072
	global_load_dwordx4 v[100:103], v[46:47], off offset:3072
	global_load_dwordx4 v[76:79], v[48:49], off
	global_load_dwordx4 v[104:107], v[54:55], off
	global_load_dwordx4 v[80:83], v[48:49], off offset:1024
	global_load_dwordx4 v[108:111], v[54:55], off offset:1024
	global_load_dwordx4 v[84:87], v[48:49], off offset:2048
	global_load_dwordx4 v[112:115], v[54:55], off offset:2048
	global_load_dwordx4 v[88:91], v[48:49], off offset:3072
	global_load_dwordx4 v[116:119], v[54:55], off offset:3072
	v_lshl_add_u64 v[50:51], v[0:1], 0, s[8:9]
	s_waitcnt vmcnt(21)
	v_pk_add_f32 v[6:7], v[6:7], 1.0 op_sel_hi:[1,0]
	v_pk_add_f32 v[4:5], v[4:5], 1.0 op_sel_hi:[1,0]
	v_pk_fma_f32 v[6:7], v[14:15], v[6:7], v[10:11]
	v_pk_fma_f32 v[4:5], v[12:13], v[4:5], v[8:9]
	s_nop 0
	v_cvt_pk_bf16_f32 v4, v4, v5
	v_cvt_pk_bf16_f32 v5, v6, v7
	global_store_dwordx2 v[50:51], v[4:5], off
	s_waitcnt vmcnt(13)
	v_pk_add_f32 v[66:67], v[66:67], 1.0 op_sel_hi:[1,0]
	v_pk_add_f32 v[64:65], v[64:65], 1.0 op_sel_hi:[1,0]
	v_pk_fma_f32 v[66:67], v[18:19], v[66:67], v[94:95]
	v_pk_fma_f32 v[64:65], v[16:17], v[64:65], v[92:93]
	s_nop 0
	v_cvt_pk_bf16_f32 v64, v64, v65
	v_cvt_pk_bf16_f32 v65, v66, v67
	global_store_dwordx2 v[50:51], v[64:65], off offset:512
	s_waitcnt vmcnt(12)
	v_pk_add_f32 v[70:71], v[70:71], 1.0 op_sel_hi:[1,0]
	v_pk_add_f32 v[68:69], v[68:69], 1.0 op_sel_hi:[1,0]
	v_pk_fma_f32 v[70:71], v[22:23], v[70:71], v[98:99]
	v_pk_fma_f32 v[68:69], v[20:21], v[68:69], v[96:97]
	s_nop 0
	v_cvt_pk_bf16_f32 v68, v68, v69
	v_cvt_pk_bf16_f32 v69, v70, v71
	global_store_dwordx2 v[50:51], v[68:69], off offset:1024
	s_waitcnt vmcnt(11)
	v_pk_add_f32 v[74:75], v[74:75], 1.0 op_sel_hi:[1,0]
	v_pk_add_f32 v[72:73], v[72:73], 1.0 op_sel_hi:[1,0]
	v_pk_fma_f32 v[74:75], v[26:27], v[74:75], v[102:103]
	v_pk_fma_f32 v[72:73], v[24:25], v[72:73], v[100:101]
	s_nop 0
	v_cvt_pk_bf16_f32 v72, v72, v73
	v_cvt_pk_bf16_f32 v73, v74, v75
	global_store_dwordx2 v[50:51], v[72:73], off offset:1536
	s_waitcnt vmcnt(10)
	v_pk_add_f32 v[78:79], v[78:79], 1.0 op_sel_hi:[1,0]
	v_pk_add_f32 v[76:77], v[76:77], 1.0 op_sel_hi:[1,0]
	v_pk_fma_f32 v[78:79], v[30:31], v[78:79], v[106:107]
	v_pk_fma_f32 v[76:77], v[28:29], v[76:77], v[104:105]
	s_nop 0
	v_cvt_pk_bf16_f32 v76, v76, v77
	v_cvt_pk_bf16_f32 v77, v78, v79
	global_store_dwordx2 v[50:51], v[76:77], off offset:2048
	s_waitcnt vmcnt(9)
	v_pk_add_f32 v[82:83], v[82:83], 1.0 op_sel_hi:[1,0]
	v_pk_add_f32 v[80:81], v[80:81], 1.0 op_sel_hi:[1,0]
	v_pk_fma_f32 v[82:83], v[34:35], v[82:83], v[110:111]
	v_pk_fma_f32 v[80:81], v[32:33], v[80:81], v[108:109]
	s_nop 0
	v_cvt_pk_bf16_f32 v80, v80, v81
	v_cvt_pk_bf16_f32 v81, v82, v83
	global_store_dwordx2 v[50:51], v[80:81], off offset:2560
	s_waitcnt vmcnt(8)
	v_pk_add_f32 v[86:87], v[86:87], 1.0 op_sel_hi:[1,0]
	v_pk_add_f32 v[84:85], v[84:85], 1.0 op_sel_hi:[1,0]
	v_pk_fma_f32 v[86:87], v[38:39], v[86:87], v[114:115]
	v_pk_fma_f32 v[84:85], v[36:37], v[84:85], v[112:113]
	s_nop 0
	v_cvt_pk_bf16_f32 v84, v84, v85
	v_cvt_pk_bf16_f32 v85, v86, v87
	global_store_dwordx2 v[50:51], v[84:85], off offset:3072
	s_waitcnt vmcnt(7)
	v_pk_add_f32 v[90:91], v[90:91], 1.0 op_sel_hi:[1,0]
	v_pk_add_f32 v[88:89], v[88:89], 1.0 op_sel_hi:[1,0]
	v_pk_fma_f32 v[90:91], v[42:43], v[90:91], v[118:119]
	v_pk_fma_f32 v[88:89], v[40:41], v[88:89], v[116:117]
	s_nop 0
	v_cvt_pk_bf16_f32 v88, v88, v89
	v_cvt_pk_bf16_f32 v89, v90, v91
	global_store_dwordx2 v[50:51], v[88:89], off offset:3584
	s_add_u32 s6, s6, s18
	s_addc_u32 s7, s7, s19
	s_cmpk_lt_i32 s6, 0x2400
	s_cbranch_scc0 .LBB0_236
